# MLA attention: softmax row sums via v_dot2c on packed P in QK gaps instead of 4 ones-fragment MFMAs per tile
# baseline (speedup 1.0000x reference)
; DI float bflo(unsigned u) { return __uint_as_float(u << 16); }
; DI float bfhi(unsigned u) { return __uint_as_float(u & 0xffff0000u); }
; DI float shx(float v, int m, int lane) { return __int_as_float(__builtin_amdgcn_ds_bpermute((lane ^ m) << 2, __float_as_int(v))); }
; template <int KW, int DQK, int DV, int MODE> ...
;     ...
;         for (int t = 1; t < NT; ++t) AD_STEP(true, (void)0);
;     }
;     ...
;     rowsum_pw(pw, ls);
;     pv_tile<DV, VP>(o, pw, lds + ((NT - 1) & 1) * VT + voff);
;     l = (ls[0] + ls[1]) + (ls[2] + ls[3]);
;     __syncthreads();
;     ...
;     l += shx(l, 32, lane);
;     if (MODE == 0) l += __int_as_float(__builtin_amdgcn_ds_bpermute((lane & 31) << 2, __float_as_int(osum[0])));
;     l_out = l;
; DI void store_y64(const f32x16 (&o)[2], float linv, bf16_t* Y, const bf16_t* proj, int token, int ycol, int hi) {
; #pragma unroll
;     for (int d0 = 0; d0 < 2; ++d0)
; #pragma unroll
;         for (int g = 0; g < 4; ++g) {
;             const int col = ycol + 32 * d0 + 8 * g + 4 * hi;
;             const u32x2 gv = *(const u32x2*)(proj + (size_t)token * LDP + C_SILU + col);
;             u32x2 w;
;             w.x = cvt_pk(o[d0][4 * g + 0] * linv * bflo(gv.x), o[d0][4 * g + 1] * linv * bfhi(gv.x));
;             w.y = cvt_pk(o[d0][4 * g + 2] * linv * bflo(gv.y), o[d0][4 * g + 3] * linv * bfhi(gv.y));
;             *(u32x2*)(Y + (size_t)token * DM + col) = w;
;         }
.LBB0_624:
	s_or_b64 exec, exec, s[6:7]
	v_exp_f32_e32 v48, v48
	v_exp_f32_e32 v49, v49
	v_exp_f32_e32 v50, v50
	v_exp_f32_e32 v51, v51
	v_exp_f32_e32 v52, v52
	v_exp_f32_e32 v53, v53
	v_cvt_pk_bf16_f32 v48, v48, v49
	v_cvt_pk_bf16_f32 v49, v50, v51
	v_exp_f32_e32 v51, v54
	v_cvt_pk_bf16_f32 v50, v52, v53
	v_exp_f32_e32 v52, v55
	v_exp_f32_e32 v53, v88
	v_exp_f32_e32 v54, v89
	v_exp_f32_e32 v55, v90
	v_exp_f32_e32 v88, v91
	v_exp_f32_e32 v89, v92
	v_exp_f32_e32 v90, v93
	v_mov_b32_e32 v92, v252
	s_mov_b32 s6, s20
	v_cvt_pk_bf16_f32 v51, v51, v52
	v_cvt_pk_bf16_f32 v52, v53, v54
	v_cvt_pk_bf16_f32 v53, v55, v88
	v_cvt_pk_bf16_f32 v54, v89, v90
	v_exp_f32_e32 v55, v80
	v_exp_f32_e32 v127, v81
	v_exp_f32_e32 v154, v82
	v_exp_f32_e32 v155, v83
	s_waitcnt vmcnt(0)
	ds_write_b128 v197, v[146:149] offset:38912
	s_waitcnt lgkmcnt(0)
	s_barrier
	ds_read_b64_tr_b16 v[122:123], v198 offset:38912
	ds_read_b64_tr_b16 v[124:125], v198 offset:40448
	ds_read_b64_tr_b16 v[132:133], v198 offset:40512
	ds_read_b64_tr_b16 v[130:131], v198 offset:38976
	ds_read_b64_tr_b16 v[134:135], v198 offset:41984
	ds_read_b64_tr_b16 v[136:137], v198 offset:43520
	ds_read_b64_tr_b16 v[118:119], v198 offset:43584
	ds_read_b64_tr_b16 v[116:117], v198 offset:42048
	ds_read_b64_tr_b16 v[138:139], v198 offset:45056
	ds_read_b64_tr_b16 v[140:141], v198 offset:46592
	ds_read_b64_tr_b16 v[90:91], v198 offset:46656
	ds_read_b64_tr_b16 v[88:89], v198 offset:45120
	ds_read_b64_tr_b16 v[142:143], v198 offset:48128
	ds_read_b64_tr_b16 v[144:145], v198 offset:49664
	ds_read_b64_tr_b16 v[82:83], v198 offset:49728
	ds_read_b64_tr_b16 v[80:81], v198 offset:48192
	s_waitcnt lgkmcnt(0)
	s_barrier
	s_lshl_b32 s7, s6, 8
	s_and_b32 s7, s7, 0x1f00
	s_add_i32 s7, s7, s30
	v_and_or_b32 v126, v92, 31, s7
	s_lshl_b32 s6, s6, 1
	v_ashrrev_i32_e32 v92, 3, v92
	s_andn2_b32 s6, s6, 63
	v_and_b32_e32 v92, -4, v92
	v_add_u32_e32 v92, s6, v92
	v_mov_b64_e32 v[120:121], s[2:3]
	v_mad_i64_i32 v[120:121], s[6:7], v126, s68, v[120:121]
	v_ashrrev_i32_e32 v93, 31, v92
	v_lshl_add_u64 v[120:121], v[120:121], 0, s[88:89]
	v_lshlrev_b64 v[150:151], 1, v[92:93]
	v_lshl_add_u64 v[146:147], v[120:121], 0, v[150:151]
	global_load_dwordx2 v[152:153], v[146:147], off
	global_load_dwordx2 v[156:157], v[146:147], off offset:16
	global_load_dwordx2 v[158:159], v[146:147], off offset:32
	global_load_dwordx2 v[160:161], v[146:147], off offset:48
	global_load_dwordx2 v[162:163], v[146:147], off offset:64
	global_load_dwordx2 v[164:165], v[146:147], off offset:80
	global_load_dwordx2 v[166:167], v[146:147], off offset:96
	global_load_dwordx2 v[168:169], v[146:147], off offset:112
	v_dot2c_f32_bf16_e32 v112, 0x3f803f80, v108
	v_dot2c_f32_bf16_e32 v113, 0x3f803f80, v109
	v_dot2c_f32_bf16_e32 v114, 0x3f803f80, v110
	v_dot2c_f32_bf16_e32 v115, 0x3f803f80, v111
	v_cvt_pk_bf16_f32 v146, v55, v127
	v_exp_f32_e32 v55, v84
	v_exp_f32_e32 v84, v85
	v_exp_f32_e32 v56, v56
	v_exp_f32_e32 v57, v57
	v_exp_f32_e32 v62, v62
	v_cvt_pk_bf16_f32 v148, v55, v84
	v_dot2c_f32_bf16_e32 v112, 0x3f803f80, v104
	v_dot2c_f32_bf16_e32 v113, 0x3f803f80, v105
	v_dot2c_f32_bf16_e32 v114, 0x3f803f80, v106
	v_dot2c_f32_bf16_e32 v115, 0x3f803f80, v107
	v_cvt_pk_bf16_f32 v104, v56, v57
	v_exp_f32_e32 v55, v60
	v_exp_f32_e32 v57, v86
	v_exp_f32_e32 v60, v87
	v_exp_f32_e32 v63, v63
	v_cvt_pk_bf16_f32 v147, v154, v155
	v_exp_f32_e32 v56, v61
	v_dot2c_f32_bf16_e32 v112, 0x3f803f80, v100
	v_dot2c_f32_bf16_e32 v113, 0x3f803f80, v101
	v_dot2c_f32_bf16_e32 v114, 0x3f803f80, v102
	v_dot2c_f32_bf16_e32 v115, 0x3f803f80, v103
	v_cvt_pk_bf16_f32 v149, v57, v60
	v_exp_f32_e32 v58, v58
	v_exp_f32_e32 v59, v59
	v_cvt_pk_bf16_f32 v107, v62, v63
	v_exp_f32_e32 v61, v94
	v_exp_f32_e32 v62, v95
	v_cvt_pk_bf16_f32 v106, v55, v56
	v_mfma_f32_32x32x16_bf16 v[32:47], v[122:125], v[146:149], v[32:47]
	v_cvt_pk_bf16_f32 v105, v58, v59
	v_mov_b32_e32 v56, v112
	v_mov_b32_e32 v58, v113
	v_mov_b32_e32 v57, v114
	v_mov_b32_e32 v59, v115
	v_cvt_pk_bf16_f32 v55, v61, v62
	v_dot2c_f32_bf16_e32 v56, 0x3f803f80, v146
	v_dot2c_f32_bf16_e32 v56, 0x3f803f80, v96
	v_dot2c_f32_bf16_e32 v58, 0x3f803f80, v97
	v_dot2c_f32_bf16_e32 v57, 0x3f803f80, v98
	v_dot2c_f32_bf16_e32 v59, 0x3f803f80, v99
	v_dot2c_f32_bf16_e32 v58, 0x3f803f80, v147
	v_dot2c_f32_bf16_e32 v57, 0x3f803f80, v148
	v_dot2c_f32_bf16_e32 v59, 0x3f803f80, v149
	v_dot2c_f32_bf16_e32 v56, 0x3f803f80, v52
	v_dot2c_f32_bf16_e32 v58, 0x3f803f80, v53
	v_dot2c_f32_bf16_e32 v57, 0x3f803f80, v54
	v_dot2c_f32_bf16_e32 v59, 0x3f803f80, v55
	v_dot2c_f32_bf16_e32 v56, 0x3f803f80, v48
	v_dot2c_f32_bf16_e32 v58, 0x3f803f80, v49
	v_dot2c_f32_bf16_e32 v57, 0x3f803f80, v50
	v_dot2c_f32_bf16_e32 v59, 0x3f803f80, v51
	v_mfma_f32_32x32x16_bf16 v[32:47], v[134:137], v[52:55], v[32:47]
	v_dot2c_f32_bf16_e32 v56, 0x3f803f80, v104
	v_dot2c_f32_bf16_e32 v58, 0x3f803f80, v105
	v_dot2c_f32_bf16_e32 v57, 0x3f803f80, v106
	v_dot2c_f32_bf16_e32 v59, 0x3f803f80, v107
	v_ashrrev_i32_e32 v127, 31, v126
	s_add_i32 s20, s20, s28
	s_cmpk_gt_i32 s20, 0xff
	v_pk_add_f32 v[56:57], v[56:57], v[58:59]
	ds_bpermute_b32 v58, v200, v64
	v_add_f32_e32 v56, v56, v57
	ds_bpermute_b32 v57, v199, v56
	v_mfma_f32_32x32x16_bf16 v[32:47], v[138:141], v[48:51], v[32:47]
	s_waitcnt lgkmcnt(0)
	v_add_f32_e32 v56, v56, v57
	v_add_f32_e32 v56, v56, v58
	v_div_scale_f32 v57, s[6:7], v56, v56, 1.0
	v_rcp_f32_e32 v58, v57
	v_mfma_f32_32x32x16_bf16 v[32:47], v[142:145], v[104:107], v[32:47]
	v_fma_f32 v59, -v57, v58, 1.0
	v_fmac_f32_e32 v58, v59, v58
	v_div_scale_f32 v59, vcc, 1.0, v56, 1.0
	v_mul_f32_e32 v60, v59, v58
	v_fma_f32 v61, -v57, v60, v59
	v_fmac_f32_e32 v60, v61, v58
	v_fma_f32 v57, -v57, v60, v59
	v_div_fmas_f32 v57, v57, v58, v60
	v_div_fixup_f32 v56, v57, v56, 1.0
	s_nop 2
	v_pk_mul_f32 v[32:33], v[32:33], v[56:57] op_sel_hi:[1,0]
	s_waitcnt vmcnt(7)
; #define LAS __attribute__((address_space(3)))
; template <int KW, int DQK, int DV, int MODE> ...
;     ...
;     bf16x8 qf[DQK / 16];
; #pragma unroll
;     for (int d0 = 0; d0 < DQK / 16; ++d0) qf[d0] = *(const bf16x8*)(Qw + (size_t)r32 * qpitch + d0 * 16 + hi * 8);
;     u32x4 kreg[KPT], vreg[VPT];
;     unsigned kgo[KPT], klo[KPT], vgo[VPT], vlo[VPT];
; #pragma unroll
;     for (int i_ = 0; i_ < KPT; ++i_) { const int c_ = tid + i_ * 512; const int key_ = c_ / KCH, part_ = c_ % KCH; kgo[i_] = (unsigned)(key_ * kpitch + part_ * 8) * 2u; klo[i_] = (unsigned)(key_ * KP + part_ * 16); }
; #pragma unroll
;     for (int i_ = 0; i_ < VPT; ++i_) { const int c_ = tid + i_ * 512; const int key_ = c_ / VCH, part_ = c_ % VCH; vgo[i_] = (unsigned)(key_ * vpitch + part_ * 8) * 2u; vlo[i_] = (unsigned)(2 * KT + key_ * VP + part_ * 16); }
;     const bool kact1 = (NKC % 512 == 0) || (tid + (KPT - 1) * 512 < NKC);
;     ...
;     float l = 0.f;
; #pragma unroll
;     for (int d0 = 0; d0 < DV / 32; ++d0)
; #pragma unroll
;         for (int r = 0; r < 16; ++r) o[d0][r] = 0.f;
;     constexpr int NT = S / 64;
;     const int koff = r32 * KP + (kco + hi * 8) * 2;
;     const int voff = 2 * KT + (4 * hi + ((lane & 15) >> 2)) * VP + (((lane >> 4) & 1) * 16 + (lane & 3) * 4) * 2;
;     { u32x4 kreg0[KPT];
;       { const char* kt_ = (const char*)Kb + (size_t)AD_TILE(0) * 64 * kpitch * 2;
;         _Pragma("unroll") for (int i_ = 0; i_ < KPT; ++i_) { if (i_ + 1 < KPT || kact1) kreg0[i_] = *(const u32x4*)(kt_ + kgo[i_]); } }
;       AD_GLOAD_K(1); AD_GLOAD_V(0);
;       _Pragma("unroll") for (int i_ = 0; i_ < KPT; ++i_) { if (i_ + 1 < KPT || kact1) *(LAS u32x4*)(lds + klo[i_]) = kreg0[i_]; } }
; DI void store_y64(const f32x16 (&o)[2], float linv, bf16_t* Y, const bf16_t* proj, int token, int ycol, int hi) {
; #pragma unroll
;     for (int d0 = 0; d0 < 2; ++d0)
; #pragma unroll
;         for (int g = 0; g < 4; ++g) {
;             const int col = ycol + 32 * d0 + 8 * g + 4 * hi;
;             const u32x2 gv = *(const u32x2*)(proj + (size_t)token * LDP + C_SILU + col);
;             u32x2 w;
;             w.x = cvt_pk(o[d0][4 * g + 0] * linv * bflo(gv.x), o[d0][4 * g + 1] * linv * bfhi(gv.x));
;             w.y = cvt_pk(o[d0][4 * g + 2] * linv * bflo(gv.y), o[d0][4 * g + 3] * linv * bfhi(gv.y));
;             *(u32x2*)(Y + (size_t)token * DM + col) = w;
;         }
	v_lshlrev_b32_e32 v60, 16, v152
	v_and_b32_e32 v61, 0xffff0000, v152
	v_pk_mul_f32 v[32:33], v[32:33], v[60:61]
	v_lshlrev_b64 v[58:59], 12, v[126:127]
	v_cvt_pk_bf16_f32 v60, v32, v33
	v_pk_mul_f32 v[32:33], v[34:35], v[56:57] op_sel_hi:[1,0]
	v_lshlrev_b32_e32 v34, 16, v153
	v_and_b32_e32 v35, 0xffff0000, v153
	v_lshl_add_u64 v[58:59], s[4:5], 0, v[58:59]
	v_pk_mul_f32 v[32:33], v[32:33], v[34:35]
	v_add_u32_e32 v34, 8, v92
	v_cvt_pk_bf16_f32 v61, v32, v33
	v_lshl_add_u64 v[32:33], v[58:59], 0, v[150:151]
	v_ashrrev_i32_e32 v35, 31, v34
	global_store_dwordx2 v[32:33], v[60:61], off
	v_lshl_add_u64 v[34:35], v[34:35], 1, v[120:121]
	v_pk_mul_f32 v[36:37], v[36:37], v[56:57] op_sel_hi:[1,0]
	v_pk_mul_f32 v[38:39], v[38:39], v[56:57] op_sel_hi:[1,0]
	v_add_u32_e32 v58, 16, v92
	v_ashrrev_i32_e32 v59, 31, v58
	v_lshl_add_u64 v[58:59], v[58:59], 1, v[120:121]
	v_mfma_f32_32x32x16_bf16 v[16:31], v[130:133], v[146:149], v[16:31]
	s_waitcnt vmcnt(7)
	v_lshlrev_b32_e32 v60, 16, v156
	v_and_b32_e32 v61, 0xffff0000, v156
	v_lshlrev_b32_e32 v34, 16, v157
	v_and_b32_e32 v35, 0xffff0000, v157
	v_pk_mul_f32 v[36:37], v[36:37], v[60:61]
	v_pk_mul_f32 v[34:35], v[38:39], v[34:35]
	v_cvt_pk_bf16_f32 v36, v36, v37
	v_cvt_pk_bf16_f32 v37, v34, v35
	global_store_dwordx2 v[32:33], v[36:37], off offset:16
	v_pk_mul_f32 v[38:39], v[40:41], v[56:57] op_sel_hi:[1,0]
	v_pk_mul_f32 v[40:41], v[42:43], v[56:57] op_sel_hi:[1,0]
	v_add_u32_e32 v36, 24, v92
	v_ashrrev_i32_e32 v37, 31, v36
	v_lshl_add_u64 v[36:37], v[36:37], 1, v[120:121]
	v_mfma_f32_32x32x16_bf16 v[16:31], v[116:119], v[52:55], v[16:31]
	s_waitcnt vmcnt(7)
	v_lshlrev_b32_e32 v42, 16, v158
	v_and_b32_e32 v43, 0xffff0000, v158
	v_lshlrev_b32_e32 v34, 16, v159
	v_and_b32_e32 v35, 0xffff0000, v159
	v_pk_mul_f32 v[38:39], v[38:39], v[42:43]
	v_pk_mul_f32 v[34:35], v[40:41], v[34:35]
	v_cvt_pk_bf16_f32 v38, v38, v39
	v_cvt_pk_bf16_f32 v39, v34, v35
	global_store_dwordx2 v[32:33], v[38:39], off offset:32
	v_pk_mul_f32 v[38:39], v[44:45], v[56:57] op_sel_hi:[1,0]
	v_pk_mul_f32 v[40:41], v[46:47], v[56:57] op_sel_hi:[1,0]
	v_add_u32_e32 v36, 32, v92
	v_ashrrev_i32_e32 v37, 31, v36
	v_lshl_add_u64 v[36:37], v[36:37], 1, v[120:121]
	v_mfma_f32_32x32x16_bf16 v[16:31], v[88:91], v[48:51], v[16:31]
	s_waitcnt vmcnt(7)
	v_lshlrev_b32_e32 v42, 16, v160
	v_and_b32_e32 v43, 0xffff0000, v160
	v_lshlrev_b32_e32 v34, 16, v161
	v_and_b32_e32 v35, 0xffff0000, v161
	v_pk_mul_f32 v[38:39], v[38:39], v[42:43]
	v_pk_mul_f32 v[34:35], v[40:41], v[34:35]
	v_cvt_pk_bf16_f32 v38, v38, v39
	v_cvt_pk_bf16_f32 v39, v34, v35
	global_store_dwordx2 v[32:33], v[38:39], off offset:48
	v_mfma_f32_32x32x16_bf16 v[16:31], v[80:83], v[104:107], v[16:31]
	v_add_u32_e32 v36, 40, v92
	v_ashrrev_i32_e32 v37, 31, v36
	v_lshl_add_u64 v[36:37], v[36:37], 1, v[120:121]
	s_waitcnt vmcnt(7)
	v_lshlrev_b32_e32 v38, 16, v162
	s_nop 6
	v_pk_mul_f32 v[16:17], v[16:17], v[56:57] op_sel_hi:[1,0]
	v_pk_mul_f32 v[18:19], v[18:19], v[56:57] op_sel_hi:[1,0]
	v_and_b32_e32 v39, 0xffff0000, v162
	v_lshlrev_b32_e32 v34, 16, v163
	v_and_b32_e32 v35, 0xffff0000, v163
	v_pk_mul_f32 v[16:17], v[16:17], v[38:39]
	v_pk_mul_f32 v[18:19], v[18:19], v[34:35]
	v_cvt_pk_bf16_f32 v16, v16, v17
	v_cvt_pk_bf16_f32 v17, v18, v19
	global_store_dwordx2 v[32:33], v[16:17], off offset:64
	v_pk_mul_f32 v[20:21], v[20:21], v[56:57] op_sel_hi:[1,0]
	v_pk_mul_f32 v[22:23], v[22:23], v[56:57] op_sel_hi:[1,0]
	v_add_u32_e32 v18, 48, v92
	v_ashrrev_i32_e32 v19, 31, v18
	v_lshl_add_u64 v[18:19], v[18:19], 1, v[120:121]
	s_waitcnt vmcnt(7)
	v_lshlrev_b32_e32 v34, 16, v164
	v_and_b32_e32 v35, 0xffff0000, v164
	v_lshlrev_b32_e32 v16, 16, v165
	v_and_b32_e32 v17, 0xffff0000, v165
	v_pk_mul_f32 v[20:21], v[20:21], v[34:35]
	v_pk_mul_f32 v[16:17], v[22:23], v[16:17]
	v_cvt_pk_bf16_f32 v20, v20, v21
	v_cvt_pk_bf16_f32 v21, v16, v17
	global_store_dwordx2 v[32:33], v[20:21], off offset:80
	v_pk_mul_f32 v[20:21], v[24:25], v[56:57] op_sel_hi:[1,0]
	v_pk_mul_f32 v[22:23], v[26:27], v[56:57] op_sel_hi:[1,0]
	v_add_u32_e32 v18, 56, v92
	v_ashrrev_i32_e32 v19, 31, v18
	v_lshl_add_u64 v[18:19], v[18:19], 1, v[120:121]
	s_waitcnt vmcnt(7)
	v_lshlrev_b32_e32 v24, 16, v166
	v_and_b32_e32 v25, 0xffff0000, v166
	v_lshlrev_b32_e32 v16, 16, v167
	v_and_b32_e32 v17, 0xffff0000, v167
	v_pk_mul_f32 v[20:21], v[20:21], v[24:25]
	v_pk_mul_f32 v[16:17], v[22:23], v[16:17]
	v_cvt_pk_bf16_f32 v20, v20, v21
	v_cvt_pk_bf16_f32 v21, v16, v17
	global_store_dwordx2 v[32:33], v[20:21], off offset:96
	v_pk_mul_f32 v[18:19], v[28:29], v[56:57] op_sel_hi:[1,0]
	v_pk_mul_f32 v[20:21], v[30:31], v[56:57] op_sel_hi:[1,0]
	s_waitcnt vmcnt(7)
	v_lshlrev_b32_e32 v22, 16, v168
	v_and_b32_e32 v23, 0xffff0000, v168
	v_lshlrev_b32_e32 v16, 16, v169
	v_and_b32_e32 v17, 0xffff0000, v169
	v_pk_mul_f32 v[18:19], v[18:19], v[22:23]
	v_pk_mul_f32 v[16:17], v[20:21], v[16:17]
	v_cvt_pk_bf16_f32 v18, v18, v19
	v_cvt_pk_bf16_f32 v19, v16, v17
	global_store_dwordx2 v[32:33], v[18:19], off offset:112
	s_cbranch_scc1 .LBB0_643
.LBB0_625:
	v_mov_b32_e32 v112, 0
	v_mov_b32_e32 v113, 0
	v_mov_b32_e32 v114, 0
	v_mov_b32_e32 v115, 0
	s_lshl_b32 s6, s20, 8
	s_ashr_i32 s10, s20, 5
	s_and_b32 s6, s6, 0x1f00
	s_add_i32 s8, s6, s30
	s_ashr_i32 s11, s10, 31
	s_lshl_b64 s[6:7], s[10:11], 13
	s_ashr_i32 s9, s8, 31
	s_add_u32 s16, s6, s8
	s_addc_u32 s17, s7, s9
	v_mov_b32_e32 v16, 0xc0
	s_mul_i32 s18, s17, 0xc0
	v_mad_u64_u32 v[16:17], s[16:17], s16, v16, v[170:171]
	v_add_u32_e32 v17, s18, v17
	s_mul_i32 s8, s10, 0x180000
	global_load_dwordx4 v[138:141], v[16:17], off offset:32
	global_load_dwordx4 v[134:137], v[16:17], off offset:64
	global_load_dwordx4 v[130:133], v[16:17], off offset:96
	global_load_dwordx4 v[120:123], v[16:17], off offset:128
	global_load_dwordx4 v[116:119], v[16:17], off offset:160
	s_mul_hi_i32 s9, s10, 0x180000
	s_add_u32 s6, s14, s8
	s_addc_u32 s7, s21, s9
	v_lshl_add_u64 v[18:19], s[6:7], 0, v[128:129]
	global_load_dwordx4 v[142:145], v[16:17], off
	global_load_dwordx4 v[20:23], v[18:19], off
	s_and_saveexec_b64 s[16:17], s[0:1]
	s_cbranch_execz .LBB0_627
	v_lshl_add_u64 v[16:17], s[6:7], 0, v[172:173]
	global_load_dwordx4 v[16:19], v[16:17], off

.LBB0_635:
	s_or_b64 exec, exec, s[8:9]
	global_load_dwordx4 v[162:165], v[184:185], off
	s_add_i32 s8, s10, -1
	s_and_b32 s11, s8, 1
	s_mul_i32 s8, s11, 0x3400
	v_add_u32_e32 v174, s8, v196
	ds_read_b128 v[80:83], v174
	ds_read_b128 v[204:207], v174 offset:32
	ds_read_b128 v[208:211], v174 offset:6656
	ds_read_b128 v[214:217], v174 offset:6688
	s_xor_b32 s8, s11, 1
	s_mulk_i32 s8, 0x3000
	v_add_u32_e32 v176, s8, v198
	s_waitcnt lgkmcnt(3)
	v_mfma_f32_32x32x16_bf16 v[96:111], v[80:83], v[142:145], v[48:63]
	v_dot2c_f32_bf16_e32 v112, 0x3f803f80, v158
	v_dot2c_f32_bf16_e32 v113, 0x3f803f80, v159
	ds_read_b128 v[222:225], v174 offset:64
	ds_read_b64_tr_b16 v[226:227], v176 offset:26624
	ds_read_b64_tr_b16 v[228:229], v176 offset:28160
	s_waitcnt lgkmcnt(4)
	v_mfma_f32_32x32x16_bf16 v[80:95], v[208:211], v[142:145], v[48:63]
	v_dot2c_f32_bf16_e32 v114, 0x3f803f80, v160
	v_dot2c_f32_bf16_e32 v115, 0x3f803f80, v161
	ds_read_b128 v[208:211], v174 offset:6720
	ds_read_b64_tr_b16 v[230:231], v176 offset:26688
	ds_read_b64_tr_b16 v[232:233], v176 offset:28224
	v_mfma_f32_32x32x16_bf16 v[96:111], v[204:207], v[138:141], v[96:111]
	v_dot2c_f32_bf16_e32 v112, 0x3f803f80, v154
	v_dot2c_f32_bf16_e32 v113, 0x3f803f80, v155
	ds_read_b128 v[204:207], v174 offset:96
	ds_read_b64_tr_b16 v[234:235], v176 offset:29696
	ds_read_b64_tr_b16 v[236:237], v176 offset:31232
	s_waitcnt lgkmcnt(9)
	v_mfma_f32_32x32x16_bf16 v[80:95], v[214:217], v[138:141], v[80:95]
	v_dot2c_f32_bf16_e32 v114, 0x3f803f80, v156
	v_dot2c_f32_bf16_e32 v115, 0x3f803f80, v157
	ds_read_b128 v[214:217], v174 offset:6752
	ds_read_b64_tr_b16 v[238:239], v176 offset:29760
	ds_read_b64_tr_b16 v[240:241], v176 offset:31296
	s_waitcnt lgkmcnt(11)
	v_mfma_f32_32x32x16_bf16 v[96:111], v[222:225], v[134:137], v[96:111]
	v_dot2c_f32_bf16_e32 v112, 0x3f803f80, v150
	v_dot2c_f32_bf16_e32 v113, 0x3f803f80, v151
	ds_read_b128 v[222:225], v174 offset:128
	ds_read_b64_tr_b16 v[242:243], v176 offset:32768
	ds_read_b64_tr_b16 v[244:245], v176 offset:34304
	s_waitcnt lgkmcnt(11)
	v_mfma_f32_32x32x16_bf16 v[80:95], v[208:211], v[134:137], v[80:95]
	v_dot2c_f32_bf16_e32 v114, 0x3f803f80, v152
	v_dot2c_f32_bf16_e32 v115, 0x3f803f80, v153
	ds_read_b128 v[208:211], v174 offset:6784
	ds_read_b64_tr_b16 v[246:247], v176 offset:32832
	ds_read_b64_tr_b16 v[248:249], v176 offset:34368
	s_waitcnt lgkmcnt(11)
	v_mfma_f32_32x32x16_bf16 v[96:111], v[204:207], v[130:133], v[96:111]
	v_dot2c_f32_bf16_e32 v112, 0x3f803f80, v146
	v_dot2c_f32_bf16_e32 v113, 0x3f803f80, v147
	ds_read_b128 v[204:207], v174 offset:160
	ds_read_b64_tr_b16 v[186:187], v176 offset:35840
	ds_read_b64_tr_b16 v[188:189], v176 offset:37376
	s_waitcnt lgkmcnt(11)
	v_mfma_f32_32x32x16_bf16 v[80:95], v[214:217], v[130:133], v[80:95]
	v_dot2c_f32_bf16_e32 v114, 0x3f803f80, v148
	v_dot2c_f32_bf16_e32 v115, 0x3f803f80, v149
	ds_read_b128 v[214:217], v174 offset:6816
	ds_read_b64_tr_b16 v[174:175], v176 offset:35904
	ds_read_b64_tr_b16 v[176:177], v176 offset:37440
	s_waitcnt lgkmcnt(11)
	v_mfma_f32_32x32x16_bf16 v[96:111], v[222:225], v[120:123], v[96:111]
	s_waitcnt lgkmcnt(8)
	v_mfma_f32_32x32x16_bf16 v[80:95], v[208:211], v[120:123], v[80:95]
	s_waitcnt lgkmcnt(5)
	v_mfma_f32_32x32x16_bf16 v[96:111], v[204:207], v[116:119], v[96:111]
	s_waitcnt lgkmcnt(2)
	v_mfma_f32_32x32x16_bf16 v[80:95], v[214:217], v[116:119], v[80:95]
	v_mfma_f32_32x32x16_bf16 v[32:47], v[226:229], v[158:161], v[32:47]
	v_mfma_f32_32x32x16_bf16 v[16:31], v[230:233], v[158:161], v[16:31]
	v_mfma_f32_32x32x16_bf16 v[32:47], v[234:237], v[154:157], v[32:47]
	v_mfma_f32_32x32x16_bf16 v[16:31], v[238:241], v[154:157], v[16:31]
	v_mfma_f32_32x32x16_bf16 v[32:47], v[242:245], v[150:153], v[32:47]
	v_mfma_f32_32x32x16_bf16 v[16:31], v[246:249], v[150:153], v[16:31]
	v_mfma_f32_32x32x16_bf16 v[32:47], v[186:189], v[146:149], v[32:47]
	s_waitcnt lgkmcnt(0)
	v_mfma_f32_32x32x16_bf16 v[16:31], v[174:177], v[146:149], v[16:31]
	s_bitcmp1_b32 s10, 0
	s_cselect_b32 s8, 0x3400, 0
	s_add_i32 s16, s8, 0
	v_add_u32_e32 v174, s16, v194
	s_waitcnt vmcnt(1)
	ds_write_b128 v174, v[166:169]
	s_and_saveexec_b64 s[8:9], s[0:1]
	v_add_u32_e32 v166, s16, v195
	ds_write_b128 v166, v[124:127]
	s_or_b64 exec, exec, s[8:9]
	v_exp_f32_e32 v166, v96
	v_exp_f32_e32 v167, v97
	v_exp_f32_e32 v98, v98
	v_exp_f32_e32 v99, v99
	v_exp_f32_e32 v168, v100
	v_exp_f32_e32 v169, v101
	v_exp_f32_e32 v174, v102
	v_exp_f32_e32 v175, v103
	v_exp_f32_e32 v104, v104
	v_exp_f32_e32 v176, v105
	v_exp_f32_e32 v105, v106
	v_exp_f32_e32 v177, v107
	v_exp_f32_e32 v106, v108
	v_exp_f32_e32 v108, v109
	v_exp_f32_e32 v107, v110
	v_exp_f32_e32 v109, v111
	v_exp_f32_e32 v80, v80
	v_exp_f32_e32 v81, v81
	v_exp_f32_e32 v82, v82
	v_exp_f32_e32 v83, v83
	v_exp_f32_e32 v84, v84
	v_exp_f32_e32 v85, v85
	v_exp_f32_e32 v86, v86
	v_exp_f32_e32 v87, v87
	v_exp_f32_e32 v88, v88
	v_exp_f32_e32 v89, v89
	v_exp_f32_e32 v90, v90
	v_exp_f32_e32 v91, v91
	v_exp_f32_e32 v92, v92
	v_exp_f32_e32 v93, v93
	v_exp_f32_e32 v94, v94
	v_exp_f32_e32 v95, v95
	s_mulk_i32 s11, 0x3000
	s_add_i32 s10, s10, 1
	s_mov_b64 s[8:9], 0x2000
	v_cvt_pk_bf16_f32 v97, v90, v91
	v_cvt_pk_bf16_f32 v96, v88, v89
	v_cvt_pk_bf16_f32 v103, v86, v87
	v_cvt_pk_bf16_f32 v102, v84, v85
	v_cvt_pk_bf16_f32 v101, v82, v83
	v_cvt_pk_bf16_f32 v100, v80, v81
	v_cvt_pk_bf16_f32 v107, v107, v109
	v_cvt_pk_bf16_f32 v106, v106, v108
	v_cvt_pk_bf16_f32 v105, v105, v177
	v_cvt_pk_bf16_f32 v104, v104, v176
	v_cvt_pk_bf16_f32 v111, v174, v175
	v_cvt_pk_bf16_f32 v110, v168, v169
	v_cvt_pk_bf16_f32 v109, v98, v99
	v_cvt_pk_bf16_f32 v108, v166, v167
	v_cvt_pk_bf16_f32 v98, v92, v93
	v_cvt_pk_bf16_f32 v99, v94, v95
	v_add_u32_e32 v80, s11, v197
	v_lshl_add_u64 v[184:185], v[184:185], 0, s[8:9]
	v_lshl_add_u64 v[190:191], v[190:191], 0, s[92:93]
	s_cmpk_eq_i32 s10, 0x80
	v_lshl_add_u64 v[192:193], v[192:193], 0, s[92:93]
	s_waitcnt vmcnt(0)
	ds_write_b128 v80, v[162:165] offset:26624
	s_waitcnt lgkmcnt(0)
	s_barrier
	s_cbranch_scc1 .LBB0_639
	v_mov_b32_e32 v158, v108
	v_mov_b32_e32 v159, v109
	v_mov_b32_e32 v160, v110
	v_mov_b32_e32 v161, v111
	v_mov_b32_e32 v154, v104
	v_mov_b32_e32 v155, v105
	v_mov_b32_e32 v156, v106
	v_mov_b32_e32 v157, v107
	v_mov_b32_e32 v150, v100
	v_mov_b32_e32 v151, v101
	v_mov_b32_e32 v152, v102
	v_mov_b32_e32 v153, v103
	v_mov_b32_e32 v146, v96
	v_mov_b32_e32 v147, v97
	v_mov_b32_e32 v148, v98
	v_mov_b32_e32 v149, v99
	global_load_dwordx4 v[166:169], v[190:191], off
	s_and_saveexec_b64 s[8:9], s[0:1]
	s_cbranch_execnz .LBB0_634
	s_branch .LBB0_635
